# dpp
# baseline (speedup 1.0000x reference)
; __global__ void __launch_bounds__(512, 2) fwd_megakernel(Params kp_) {
;     ...
;                                 { const int key = tid >> 3, ch = tid & 7;
;                                   const u32x4 kw = kwn, vw = vwn;
;                                   float kf[8]; float ss = 0.f;
; #pragma unroll
;                                   for (int e = 0; e < 4; ++e) { kf[2 * e] = bflo(kw[e]); kf[2 * e + 1] = bfhi(kw[e]); }
; #pragma unroll
;                                   for (int e = 0; e < 8; ++e) ss += kf[e] * kf[e];
;                                   ss += SHX(ss, 1); ss += SHX(ss, 2); ss += SHX(ss, 4);
;                                   const float rk = rsqrtf(ss * (1.f / 64.f) + EPS);
;                                   const f32x4 g0 = *(const f32x4*)(gk + ch * 8), g1 = *(const f32x4*)(gk + ch * 8 + 4);
;                                   u32x4 kp; kp.x = pk2(kf[0] * rk * g0.x, kf[1] * rk * g0.y); kp.y = pk2(kf[2] * rk * g0.z, kf[3] * rk * g0.w); kp.z = pk2(kf[4] * rk * g1.x, kf[5] * rk * g1.y); kp.w = pk2(kf[6] * rk * g1.z, kf[7] * rk * g1.w);
;                                   *(u32x4*)(Kb + key * 72 + ch * 8) = kp;
; #pragma unroll
;                                   for (int e = 0; e < 4; ++e) { VTb[(ch * 8 + 2 * e) * 72 + key] = (bf16)(vw[e] & 0xffffu); VTb[(ch * 8 + 2 * e + 1) * 72 + key] = (bf16)(vw[e] >> 16); } }
;                                 LBAR();
;                                 { const int key = tid >> 3, ch = tid & 7; const size_t krow = (size_t)b * SEQ + (kti > 0 ? kbase - 64 : kbase) + key;
;                                   kwn = *(const u32x4*)(proj + krow * HYBN + 2560 + h * 64 + ch * 8); vwn = *(const u32x4*)(proj + krow * HYBN + 3072 + h * 64 + ch * 8); }
;                                 const bool walive = __any((Rq[0] <= 120.f) || (Rq[1] <= 120.f)) != 0;
;                                 if (kbase < tq0 + 31 && walive) {
; #pragma unroll
;                                     for (int qt = 0; qt < 2; ++qt) {
;                                         f32x4 sa[4];
; #pragma unroll
;                                         for (int kt = 0; kt < 4; ++kt) { sa[kt] = (f32x4){0.f, 0.f, 0.f, 0.f};
; #pragma unroll
;                                             for (int ks = 0; ks < 2; ++ks) sa[kt] = MFMA16(*(const bf16x8*)(Kb + (kt * 16 + r16) * 72 + ks * 32 + g4 * 8), qf[qt][ks], sa[kt]); }
.LBB0_891:
	global_load_dwordx4 v[56:59], v[118:119], off offset:16
	global_load_dwordx4 v[60:63], v[118:119], off
	s_waitcnt vmcnt(2)
	v_lshlrev_b32_e32 v74, 16, v52
	v_and_b32_e32 v75, 0xffff0000, v52
	v_lshlrev_b32_e32 v70, 16, v53
	v_and_b32_e32 v71, 0xffff0000, v53
	v_pk_mul_f32 v[52:53], v[74:75], v[74:75]
	v_pk_mul_f32 v[72:73], v[70:71], v[70:71]
	v_add_f32_e32 v52, v52, v53
	v_lshlrev_b32_e32 v68, 16, v54
	v_and_b32_e32 v69, 0xffff0000, v54
	v_add_f32_e32 v52, v52, v72
	v_lshlrev_b32_e32 v64, 16, v55
	v_and_b32_e32 v65, 0xffff0000, v55
	v_pk_mul_f32 v[54:55], v[68:69], v[68:69]
	v_add_f32_e32 v52, v52, v73
	v_add_f32_e32 v52, v52, v54
	v_pk_mul_f32 v[66:67], v[64:65], v[64:65]
	v_add_f32_e32 v52, v52, v55
	v_add_f32_e32 v52, v52, v66
	v_add_f32_e32 v52, v52, v67
	s_nop 1
	v_mov_b32_dpp v53, v52 quad_perm:[1,0,3,2] row_mask:0xf bank_mask:0xf
	s_add_i32 s0, s3, 64
	s_waitcnt lgkmcnt(0)
	v_add_f32_e32 v52, v52, v53
	s_nop 1
	v_mov_b32_dpp v53, v52 quad_perm:[2,3,0,1] row_mask:0xf bank_mask:0xf
	s_waitcnt lgkmcnt(0)
	v_add_f32_e32 v52, v52, v53
	s_nop 1
	v_mov_b32_dpp v53, v52 row_half_mirror row_mask:0xf bank_mask:0xf
	s_waitcnt lgkmcnt(0)
	v_add_f32_e32 v52, v52, v53
	v_fmamk_f32 v52, v52, 0x3c800000, v198
	v_cmp_gt_f32_e32 vcc, s65, v52
	v_mul_f32_e32 v53, 0x4b800000, v52
	s_nop 0
	v_cndmask_b32_e32 v52, v52, v53, vcc
	v_rsq_f32_e32 v52, v52
	s_nop 0
	v_mul_f32_e32 v53, 0x45800000, v52
	v_cndmask_b32_e32 v66, v52, v53, vcc
	v_pk_mul_f32 v[52:53], v[66:67], v[74:75] op_sel_hi:[0,1]
	v_pk_mul_f32 v[54:55], v[66:67], v[70:71] op_sel_hi:[0,1]
	v_subrev_co_u32_e32 v218, vcc, 1, v129
	s_and_b64 s[14:15], vcc, exec
	s_cselect_b32 s14, 0, s3
	s_ashr_i32 s15, s14, 31
	s_lshl_b32 s94, s49, 1
	s_waitcnt vmcnt(0)
	v_pk_mul_f32 v[52:53], v[60:61], v[52:53]
	v_pk_mul_f32 v[54:55], v[62:63], v[54:55]
	v_cvt_pk_bf16_f32 v52, v52, v53
	v_cvt_pk_bf16_f32 v53, v54, v55
	v_pk_mul_f32 v[54:55], v[66:67], v[68:69] op_sel_hi:[0,1]
	v_pk_mul_f32 v[54:55], v[56:57], v[54:55]
	v_pk_mul_f32 v[56:57], v[66:67], v[64:65] op_sel_hi:[0,1]
	v_pk_mul_f32 v[56:57], v[58:59], v[56:57]
	v_cvt_pk_bf16_f32 v54, v54, v55
	v_cvt_pk_bf16_f32 v55, v56, v57
	ds_write_b128 v215, v[52:55]
	ds_write_b16 v213, v48 offset:9216
	ds_write_b16_d16_hi v214, v48 offset:9360
	ds_write_b16 v213, v49 offset:9504
	ds_write_b16_d16_hi v214, v49 offset:9648
	ds_write_b16 v213, v50 offset:9792
	ds_write_b16_d16_hi v214, v50 offset:9936
	ds_write_b16 v213, v51 offset:10080
	ds_write_b16_d16_hi v214, v51 offset:10224
	v_lshl_add_u64 v[48:49], v[122:123], 0, s[14:15]
	v_mov_b64_e32 v[50:51], s[52:53]
	v_mad_u64_u32 v[50:51], s[14:15], v48, s70, v[50:51]
	v_mad_i32_i24 v51, v49, s70, v51
	v_lshl_add_u64 v[48:49], v[50:51], 0, s[94:95]
	v_lshl_add_u64 v[48:49], v[48:49], 0, v[196:197]
	v_add_co_u32_e32 v48, vcc, s64, v48
	s_waitcnt lgkmcnt(0)
	s_barrier
	v_max_f32_e32 v56, v130, v130
	s_nop 0
	v_addc_co_u32_e32 v49, vcc, 0, v49, vcc
	global_load_dwordx4 v[52:55], v[48:49], off offset:1024
	s_nop 0
	global_load_dwordx4 v[48:51], v[48:49], off offset:2048
	v_max_f32_e32 v57, v131, v131
	v_min_f32_e32 v56, v57, v56
	v_cmp_ge_f32_e32 vcc, s74, v56
	s_cmp_eq_u64 vcc, 0
	s_cselect_b64 s[14:15], -1, 0
	s_cmp_ge_i32 s0, s2
	s_cselect_b64 s[0:1], -1, 0
	s_or_b64 s[0:1], s[0:1], s[14:15]
	s_and_b64 vcc, exec, s[0:1]
	s_cbranch_vccnz .LBB0_893
	ds_read_b128 v[80:83], v216
	ds_read_b128 v[72:75], v216 offset:64
	ds_read_b128 v[76:79], v216 offset:2304
	ds_read_b128 v[68:71], v216 offset:2368
	ds_read_b128 v[92:95], v216 offset:4608
	ds_read_b128 v[84:87], v216 offset:4672
	ds_read_b128 v[108:111], v216 offset:6912
	ds_read_b128 v[100:103], v216 offset:6976
	s_waitcnt lgkmcnt(7)
	v_mfma_f32_16x16x32_bf16 v[56:59], v[80:83], v[0:3], 0
	v_add_u32_e32 v104, s3, v205
	v_add_u32_e32 v219, 64, v104
	v_add_u32_e32 v221, 0x41, v104
	s_waitcnt lgkmcnt(6)
	v_mfma_f32_16x16x32_bf16 v[88:91], v[72:75], v[4:7], v[56:59]
	v_add_u32_e32 v223, 0x50, v104
	v_add_u32_e32 v222, 0x51, v104
	v_add_u32_e32 v220, 0x60, v104
	s_waitcnt lgkmcnt(5)
	v_mfma_f32_16x16x32_bf16 v[60:63], v[76:79], v[0:3], 0
	v_add_u32_e32 v227, 0x61, v104
	s_nop 1
	v_mul_f32_e64 v56, |v88|, s68
	v_exp_f32_e32 v56, v56
	s_waitcnt lgkmcnt(3)
	v_mfma_f32_16x16x32_bf16 v[96:99], v[92:95], v[0:3], 0
	v_mul_f32_e64 v106, |v89|, s68
	v_max_f32_e32 v105, v88, v88
	v_add_f32_e32 v56, 1.0, v56
	v_cmp_gt_f32_e32 vcc, s65, v56
	v_mfma_f32_16x16x32_bf16 v[64:67], v[68:71], v[4:7], v[60:63]
	v_max_f32_e32 v133, 0, v105
	v_cndmask_b32_e64 v57, 0, 32, vcc
	v_ldexp_f32 v56, v56, v57
	s_waitcnt lgkmcnt(2)
	v_mfma_f32_16x16x32_bf16 v[60:63], v[84:87], v[4:7], v[96:99]
	v_add_u32_e32 v228, 0x70, v104
	v_add_u32_e32 v229, 0x71, v104
	v_add_u32_e32 v230, 0x72, v104
	v_log_f32_e32 v96, v56
	v_exp_f32_e32 v97, v106
	s_waitcnt lgkmcnt(1)
	v_mfma_f32_16x16x32_bf16 v[56:59], v[108:111], v[0:3], 0
	v_add_u32_e32 v231, 0x73, v104
	v_mul_f32_e32 v98, 0x3f317217, v96
	v_fma_f32 v98, v96, s72, -v98
	v_fmac_f32_e32 v98, 0x3377d1cf, v96
	v_fmac_f32_e32 v98, 0x3f317217, v96
	v_cmp_lt_f32_e64 s[0:1], |v96|, s73
	s_waitcnt lgkmcnt(0)
; __device__ __forceinline__ float softplusf(float z) { return fmaxf(z, 0.f) + __logf(1.f + __expf(-fabsf(z))); }
; #define MFMA16(a, b, c) __builtin_amdgcn_mfma_f32_16x16x32_bf16((a), (b), (c), 0, 0, 0)
; __global__ void __launch_bounds__(512, 2) fwd_megakernel(Params kp_) {
;     ...
;                                         f32x4 sa[4];
; #pragma unroll
;                                         for (int kt = 0; kt < 4; ++kt) { sa[kt] = (f32x4){0.f, 0.f, 0.f, 0.f};
; #pragma unroll
;                                             for (int ks = 0; ks < 2; ++ks) sa[kt] = MFMA16(*(const bf16x8*)(Kb + (kt * 16 + r16) * 72 + ks * 32 + g4 * 8), qf[qt][ks], sa[kt]); }
;                                         const int tqi = tq0 + qt * 16 + r16;
;                                         float T[4];
; #pragma unroll
;                                         for (int kt = 0; kt < 4; ++kt) {
;                                             float sp[4];
; #pragma unroll
;                                             for (int j = 0; j < 4; ++j) { const float z = sa[kt][j]; const bool act = (kbase + kt * 16 + g4 * 4 + j) < tqi; const float s1 = softplusf(z);
;                                                 sp[j] = act ? s1 : 0.f; sa[kt][j] = act ? (z - s1) : -1e30f; }
;                                             const float s2 = sp[3], s1b = s2 + sp[2], s0 = s1b + sp[1];
;                                             T[kt] = s0 + sp[0];
;                                             sa[kt][0] -= s0; sa[kt][1] -= s1b; sa[kt][2] -= s2;
;                                         }
	v_mfma_f32_16x16x32_bf16 v[56:59], v[100:103], v[4:7], v[56:59]
	v_add_u32_e32 v132, 0x2000, v217
	v_cndmask_b32_e64 v96, v96, v98, s[0:1]
	v_cndmask_b32_e32 v98, 0, v244, vcc
	v_sub_f32_e32 v137, v96, v98
	v_add_f32_e32 v96, 1.0, v97
	v_cmp_gt_f32_e32 vcc, s65, v96
	v_mul_f32_e64 v98, |v90|, s68
	v_exp_f32_e32 v98, v98
	v_cndmask_b32_e64 v97, 0, 32, vcc
	v_ldexp_f32 v96, v96, v97
	v_log_f32_e32 v96, v96
	v_max_f32_e32 v97, v89, v89
	v_max_f32_e32 v135, 0, v97
	v_add_f32_e32 v98, 1.0, v98
	v_mul_f32_e32 v97, 0x3f317217, v96
	v_fma_f32 v97, v96, s72, -v97
	v_fmac_f32_e32 v97, 0x3377d1cf, v96
	v_fmac_f32_e32 v97, 0x3f317217, v96
	v_cmp_lt_f32_e64 s[0:1], |v96|, s73
	v_mfma_f32_16x16x32_bf16 v[80:83], v[80:83], v[8:11], 0
	v_add_u32_e32 v224, 0x2800, v217
	v_cndmask_b32_e64 v96, v96, v97, s[0:1]
	v_cndmask_b32_e32 v97, 0, v244, vcc
	v_cmp_gt_f32_e32 vcc, s65, v98
	v_sub_f32_e32 v141, v96, v97
	v_mul_f32_e64 v97, |v91|, s68
	v_cndmask_b32_e64 v99, 0, 32, vcc
	v_ldexp_f32 v98, v98, v99
	v_log_f32_e32 v98, v98
	v_max_f32_e32 v96, v90, v90
	v_exp_f32_e32 v97, v97
	v_max_f32_e32 v139, 0, v96
	v_mul_f32_e32 v96, 0x3f317217, v98
	v_fma_f32 v96, v98, s72, -v96
	v_fmac_f32_e32 v96, 0x3377d1cf, v98
	v_fmac_f32_e32 v96, 0x3f317217, v98
	v_cmp_lt_f32_e64 s[0:1], |v98|, s73
	v_add_f32_e32 v97, 1.0, v97
	v_mfma_f32_16x16x32_bf16 v[104:107], v[72:75], v[20:23], v[80:83]
	v_cndmask_b32_e64 v96, v98, v96, s[0:1]
	v_cndmask_b32_e32 v98, 0, v244, vcc
	v_cmp_gt_f32_e32 vcc, s65, v97
	v_sub_f32_e32 v147, v96, v98
	v_max_f32_e32 v96, v91, v91
	v_cndmask_b32_e64 v99, 0, 32, vcc
	v_ldexp_f32 v97, v97, v99
	v_log_f32_e32 v97, v97
	v_max_f32_e32 v145, 0, v96
	v_mul_f32_e64 v98, |v64|, s68
	v_exp_f32_e32 v98, v98
	v_mul_f32_e32 v96, 0x3f317217, v97
	v_fma_f32 v96, v97, s72, -v96
	v_fmac_f32_e32 v96, 0x3377d1cf, v97
	v_fmac_f32_e32 v96, 0x3f317217, v97
	v_cmp_lt_f32_e64 s[0:1], |v97|, s73
	v_mfma_f32_16x16x32_bf16 v[72:75], v[76:79], v[8:11], 0
	v_add_u32_e32 v225, 0x3000, v217
	v_cndmask_b32_e64 v96, v97, v96, s[0:1]
	v_cndmask_b32_e32 v97, 0, v244, vcc
	v_sub_f32_e32 v153, v96, v97
	v_add_f32_e32 v96, 1.0, v98
	v_cmp_gt_f32_e32 vcc, s65, v96
	v_mul_f32_e64 v98, |v65|, s68
	v_exp_f32_e32 v98, v98
	v_cndmask_b32_e64 v97, 0, 32, vcc
	v_ldexp_f32 v96, v96, v97
	v_log_f32_e32 v96, v96
	v_max_f32_e32 v97, v64, v64
	v_max_f32_e32 v143, 0, v97
	v_mfma_f32_16x16x32_bf16 v[108:111], v[108:111], v[8:11], 0
	v_mul_f32_e32 v97, 0x3f317217, v96
	v_fma_f32 v97, v96, s72, -v97
	v_fmac_f32_e32 v97, 0x3377d1cf, v96
	v_fmac_f32_e32 v97, 0x3f317217, v96
	v_cmp_lt_f32_e64 s[0:1], |v96|, s73
	v_add_u32_e32 v226, 0x3800, v217
	v_mfma_f32_16x16x32_bf16 v[100:103], v[100:103], v[20:23], v[108:111]
	v_cndmask_b32_e64 v96, v96, v97, s[0:1]
	v_cndmask_b32_e32 v97, 0, v244, vcc
	v_sub_f32_e32 v151, v96, v97
	v_add_f32_e32 v96, 1.0, v98
	v_cmp_gt_f32_e32 vcc, s65, v96
	v_mul_f32_e64 v98, |v66|, s68
	v_exp_f32_e32 v98, v98
	v_cndmask_b32_e64 v97, 0, 32, vcc
	v_ldexp_f32 v96, v96, v97
	v_log_f32_e32 v96, v96
	v_max_f32_e32 v97, v65, v65
	v_max_f32_e32 v149, 0, v97
	v_add_f32_e32 v98, 1.0, v98
	v_mul_f32_e32 v97, 0x3f317217, v96
	v_fma_f32 v97, v96, s72, -v97
	v_fmac_f32_e32 v97, 0x3377d1cf, v96
	v_fmac_f32_e32 v97, 0x3f317217, v96
	v_cmp_lt_f32_e64 s[0:1], |v96|, s73
	v_mul_f32_e64 v109, |v105|, s68
	v_exp_f32_e32 v109, v109
	v_cndmask_b32_e64 v96, v96, v97, s[0:1]
	v_cndmask_b32_e32 v97, 0, v244, vcc
	v_cmp_gt_f32_e32 vcc, s65, v98
	v_sub_f32_e32 v157, v96, v97
	v_mul_f32_e64 v97, |v67|, s68
	v_cndmask_b32_e64 v99, 0, 32, vcc
	v_ldexp_f32 v98, v98, v99
	v_log_f32_e32 v98, v98
	v_max_f32_e32 v96, v66, v66
	v_exp_f32_e32 v97, v97
	v_max_f32_e32 v155, 0, v96
	v_mul_f32_e32 v96, 0x3f317217, v98
	v_fma_f32 v96, v98, s72, -v96
	v_fmac_f32_e32 v96, 0x3377d1cf, v98
	v_fmac_f32_e32 v96, 0x3f317217, v98
	v_cmp_lt_f32_e64 s[0:1], |v98|, s73
	v_add_f32_e32 v97, 1.0, v97
	v_max_f32_e32 v108, v104, v104
	v_cndmask_b32_e64 v96, v98, v96, s[0:1]
	v_cndmask_b32_e32 v98, 0, v244, vcc
	v_cmp_gt_f32_e32 vcc, s65, v97
	v_sub_f32_e32 v163, v96, v98
	v_max_f32_e32 v96, v67, v67
	v_cndmask_b32_e64 v99, 0, 32, vcc
	v_ldexp_f32 v97, v97, v99
	v_log_f32_e32 v97, v97
	v_max_f32_e32 v161, 0, v96
	v_mul_f32_e64 v98, |v60|, s68
	v_exp_f32_e32 v98, v98
	v_mul_f32_e32 v96, 0x3f317217, v97
	v_fma_f32 v96, v97, s72, -v96
	v_fmac_f32_e32 v96, 0x3377d1cf, v97
	v_fmac_f32_e32 v96, 0x3f317217, v97
	v_cmp_lt_f32_e64 s[0:1], |v97|, s73
	v_add_f32_e32 v109, 1.0, v109
	v_cmp_lt_i32_e64 s[24:25], v219, v117
	v_cndmask_b32_e64 v96, v97, v96, s[0:1]
	v_cndmask_b32_e32 v97, 0, v244, vcc
	v_sub_f32_e32 v169, v96, v97
	v_add_f32_e32 v96, 1.0, v98
	v_cmp_gt_f32_e32 vcc, s65, v96
	v_mul_f32_e64 v98, |v61|, s68
	v_exp_f32_e32 v98, v98
	v_cndmask_b32_e64 v97, 0, 32, vcc
	v_ldexp_f32 v96, v96, v97
	v_log_f32_e32 v96, v96
	v_max_f32_e32 v97, v60, v60
	v_max_f32_e32 v159, 0, v97
	v_cmp_lt_i32_e64 s[40:41], v223, v125
	v_mul_f32_e32 v97, 0x3f317217, v96
	v_fma_f32 v97, v96, s72, -v97
	v_fmac_f32_e32 v97, 0x3377d1cf, v96
	v_fmac_f32_e32 v97, 0x3f317217, v96
	v_cmp_lt_f32_e64 s[0:1], |v96|, s73
	v_cmp_lt_i32_e64 s[18:19], v222, v124
	v_cmp_lt_i32_e64 s[44:45], v220, v117
	v_cndmask_b32_e64 v96, v96, v97, s[0:1]
	v_cndmask_b32_e32 v97, 0, v244, vcc
	v_sub_f32_e32 v167, v96, v97
	v_add_f32_e32 v96, 1.0, v98
	v_cmp_gt_f32_e32 vcc, s65, v96
	v_mul_f32_e64 v98, |v62|, s68
	v_exp_f32_e32 v98, v98
	v_cndmask_b32_e64 v97, 0, 32, vcc
	v_ldexp_f32 v96, v96, v97
	v_log_f32_e32 v96, v96
	v_max_f32_e32 v97, v61, v61
	v_max_f32_e32 v165, 0, v97
	v_add_f32_e32 v98, 1.0, v98
	v_mul_f32_e32 v97, 0x3f317217, v96
	v_fma_f32 v97, v96, s72, -v97
	v_fmac_f32_e32 v97, 0x3377d1cf, v96
; __global__ void __launch_bounds__(512, 2) fwd_megakernel(Params kp_) {
;     ...
;                                         for (int kt = 0; kt < 4; ++kt) {
;                                             float sp[4];
; #pragma unroll
;                                             for (int j = 0; j < 4; ++j) { const float z = sa[kt][j]; const bool act = (kbase + kt * 16 + g4 * 4 + j) < tqi; const float s1 = softplusf(z);
;                                                 sp[j] = act ? s1 : 0.f; sa[kt][j] = act ? (z - s1) : -1e30f; }
;                                             const float s2 = sp[3], s1b = s2 + sp[2], s0 = s1b + sp[1];
;                                             T[kt] = s0 + sp[0];
;                                             sa[kt][0] -= s0; sa[kt][1] -= s1b; sa[kt][2] -= s2;
;                                         }
;                                         float kacc = Rq[qt];
; #pragma unroll
;     ...
;                                             const float d1 = SHD(T[kt], 16), d2 = SHD(T[kt], 32), d3 = SHD(T[kt], 48);
;                                             const float E = (g4 < 3 ? d1 : 0.f) + (g4 < 2 ? d2 : 0.f) + (g4 < 1 ? d3 : 0.f);
;                                             const float off = kacc + E;
; #pragma unroll
;                                             for (int j = 0; j < 4; ++j) sa[kt][j] = __expf(sa[kt][j] - off);
;                                             float tt = T[kt]; tt += SHX(tt, 16); tt += SHX(tt, 32);
;                                             kacc += tt;
;                                         }
;                                         Rq[qt] = kacc;
; #pragma unroll
;                                         for (int hf = 0; hf < 2; ++hf) {
;                                             u32x4 pw; pw.x = pk2(sa[2 * hf][0], sa[2 * hf][1]); pw.y = pk2(sa[2 * hf][2], sa[2 * hf][3]); pw.z = pk2(sa[2 * hf + 1][0], sa[2 * hf + 1][1]); pw.w = pk2(sa[2 * hf + 1][2], sa[2 * hf + 1][3]);
;                                             const bf16x8 pb = __builtin_bit_cast(bf16x8, pw);
; #pragma unroll
;                                             for (int dt = 0; dt < 4; ++dt) {
;                                                 const bf16* vp = VTb + (dt * 16 + r16) * 72 + hf * 32 + g4 * 4;
;                                                 const u32x2 v0 = *(const u32x2*)vp, v1 = *(const u32x2*)(vp + 16);
	v_fmac_f32_e32 v97, 0x3f317217, v96
	v_cmp_lt_f32_e64 s[0:1], |v96|, s73
	v_cmp_lt_i32_e64 s[26:27], v227, v124
	v_cmp_lt_i32_e64 s[34:35], v229, v117
	v_cndmask_b32_e64 v96, v96, v97, s[0:1]
	v_cndmask_b32_e32 v97, 0, v244, vcc
	v_cmp_gt_f32_e32 vcc, s65, v98
	v_sub_f32_e32 v173, v96, v97
	v_mul_f32_e64 v97, |v63|, s68
	v_cndmask_b32_e64 v99, 0, 32, vcc
	v_ldexp_f32 v98, v98, v99
	v_log_f32_e32 v98, v98
	v_max_f32_e32 v96, v62, v62
	v_exp_f32_e32 v97, v97
	v_max_f32_e32 v171, 0, v96
	v_mul_f32_e32 v96, 0x3f317217, v98
	v_fma_f32 v96, v98, s72, -v96
	v_fmac_f32_e32 v96, 0x3377d1cf, v98
	v_fmac_f32_e32 v96, 0x3f317217, v98
	v_cmp_lt_f32_e64 s[0:1], |v98|, s73
	v_add_f32_e32 v97, 1.0, v97
	v_cmp_lt_i32_e64 s[38:39], v230, v117
	v_cndmask_b32_e64 v96, v98, v96, s[0:1]
	v_cndmask_b32_e32 v98, 0, v244, vcc
	v_cmp_gt_f32_e32 vcc, s65, v97
	v_sub_f32_e32 v179, v96, v98
	v_max_f32_e32 v96, v63, v63
	v_cndmask_b32_e64 v99, 0, 32, vcc
	v_ldexp_f32 v97, v97, v99
	v_log_f32_e32 v97, v97
	v_max_f32_e32 v177, 0, v96
	v_mul_f32_e64 v98, |v56|, s68
	v_exp_f32_e32 v98, v98
	v_mul_f32_e32 v96, 0x3f317217, v97
	v_fma_f32 v96, v97, s72, -v96
	v_fmac_f32_e32 v96, 0x3377d1cf, v97
	v_fmac_f32_e32 v96, 0x3f317217, v97
	v_cmp_lt_f32_e64 s[0:1], |v97|, s73
	v_cmp_lt_i32_e64 s[36:37], v231, v117
	v_cmp_lt_i32_e64 s[42:43], v228, v124
	v_cndmask_b32_e64 v96, v97, v96, s[0:1]
	v_cndmask_b32_e32 v97, 0, v244, vcc
	v_sub_f32_e32 v185, v96, v97
	v_add_f32_e32 v96, 1.0, v98
	v_cmp_gt_f32_e32 vcc, s65, v96
	v_mul_f32_e64 v98, |v57|, s68
	v_exp_f32_e32 v98, v98
	v_cndmask_b32_e64 v97, 0, 32, vcc
	v_ldexp_f32 v96, v96, v97
	v_log_f32_e32 v96, v96
	v_max_f32_e32 v97, v56, v56
	v_max_f32_e32 v175, 0, v97
	v_mul_f32_e32 v97, 0x3f317217, v96
	v_fma_f32 v97, v96, s72, -v97
	v_fmac_f32_e32 v97, 0x3377d1cf, v96
	v_fmac_f32_e32 v97, 0x3f317217, v96
	v_cmp_lt_f32_e64 s[0:1], |v96|, s73
	s_nop 1
	v_cndmask_b32_e64 v96, v96, v97, s[0:1]
	v_cndmask_b32_e32 v97, 0, v244, vcc
	v_sub_f32_e32 v183, v96, v97
	v_add_f32_e32 v96, 1.0, v98
	v_cmp_gt_f32_e32 vcc, s65, v96
	v_mul_f32_e64 v98, |v58|, s68
	v_exp_f32_e32 v98, v98
	v_cndmask_b32_e64 v97, 0, 32, vcc
	v_ldexp_f32 v96, v96, v97
	v_log_f32_e32 v96, v96
	v_max_f32_e32 v97, v57, v57
	v_max_f32_e32 v181, 0, v97
	v_mul_f32_e32 v97, 0x3f317217, v96
	v_fma_f32 v97, v96, s72, -v97
	v_fmac_f32_e32 v97, 0x3377d1cf, v96
	v_fmac_f32_e32 v97, 0x3f317217, v96
	v_cmp_lt_f32_e64 s[0:1], |v96|, s73
	s_nop 1
	v_cndmask_b32_e64 v96, v96, v97, s[0:1]
	v_cndmask_b32_e32 v97, 0, v244, vcc
	v_sub_f32_e32 v189, v96, v97
	v_add_f32_e32 v96, 1.0, v98
	v_cmp_gt_f32_e32 vcc, s65, v96
	s_nop 1
	v_cndmask_b32_e64 v97, 0, 32, vcc
	v_ldexp_f32 v96, v96, v97
	v_log_f32_e32 v96, v96
	v_max_f32_e32 v97, v58, v58
	v_max_f32_e32 v187, 0, v97
	v_cndmask_b32_e32 v98, 0, v244, vcc
	v_mul_f32_e32 v97, 0x3f317217, v96
	v_fma_f32 v97, v96, s72, -v97
	v_fmac_f32_e32 v97, 0x3377d1cf, v96
	v_fmac_f32_e32 v97, 0x3f317217, v96
	v_cmp_lt_f32_e64 s[0:1], |v96|, s73
	s_nop 1
	v_cndmask_b32_e64 v96, v96, v97, s[0:1]
	v_mul_f32_e64 v97, |v59|, s68
	v_exp_f32_e32 v97, v97
	v_sub_f32_e32 v193, v96, v98
	v_add_f32_e32 v96, 1.0, v97
	v_cmp_gt_f32_e32 vcc, s65, v96
	s_nop 1
	v_cndmask_b32_e64 v97, 0, 32, vcc
	v_ldexp_f32 v96, v96, v97
	v_log_f32_e32 v96, v96
	v_max_f32_e32 v97, v59, v59
	v_max_f32_e32 v191, 0, v97
	v_cndmask_b32_e32 v76, 0, v244, vcc
	v_mul_f32_e32 v97, 0x3f317217, v96
	v_fma_f32 v97, v96, s72, -v97
	v_fmac_f32_e32 v97, 0x3377d1cf, v96
	v_fmac_f32_e32 v97, 0x3f317217, v96
	v_cmp_lt_f32_e64 s[0:1], |v96|, s73
	s_nop 1
	v_cndmask_b32_e64 v80, v96, v97, s[0:1]
	v_mfma_f32_16x16x32_bf16 v[96:99], v[68:71], v[20:23], v[72:75]
	v_sub_f32_e32 v195, v80, v76
	ds_read2_b64 v[80:83], v132 offset0:128 offset1:132
	ds_read2_b64 v[76:79], v224 offset0:160 offset1:164
	v_mfma_f32_16x16x32_bf16 v[68:71], v[92:95], v[8:11], 0
	ds_read2_b64 v[72:75], v225 offset0:192 offset1:196
	v_mfma_f32_16x16x32_bf16 v[92:95], v[84:87], v[20:23], v[68:71]
	s_nop 5
	v_mul_f32_e64 v68, |v104|, s68
	v_exp_f32_e32 v134, v68
	ds_read2_b64 v[84:87], v226 offset0:224 offset1:228
	ds_read2_b64 v[68:71], v132 offset0:136 offset1:140
	v_add_f32_e32 v132, 1.0, v134
	v_cmp_gt_f32_e32 vcc, s65, v132
	s_nop 1
	v_cndmask_b32_e64 v134, 0, 32, vcc
	v_ldexp_f32 v132, v132, v134
	v_log_f32_e32 v134, v132
	v_max_f32_e32 v132, 0, v108
	v_cndmask_b32_e32 v110, 0, v244, vcc
	v_cmp_gt_f32_e32 vcc, s65, v109
	v_mul_f32_e32 v108, 0x3f317217, v134
	v_fma_f32 v108, v134, s72, -v108
	v_cndmask_b32_e64 v111, 0, 32, vcc
	v_fmac_f32_e32 v108, 0x3377d1cf, v134
	v_ldexp_f32 v109, v109, v111
	v_fmac_f32_e32 v108, 0x3f317217, v134
	v_cmp_lt_f32_e64 s[0:1], |v134|, s73
	v_log_f32_e32 v109, v109
	s_nop 0
	v_cndmask_b32_e64 v108, v134, v108, s[0:1]
	v_sub_f32_e32 v136, v108, v110
	v_mul_f32_e64 v110, |v106|, s68
	v_max_f32_e32 v108, v105, v105
	v_exp_f32_e32 v110, v110
	v_max_f32_e32 v134, 0, v108
	v_mul_f32_e32 v108, 0x3f317217, v109
	v_fma_f32 v108, v109, s72, -v108
	v_fmac_f32_e32 v108, 0x3377d1cf, v109
	v_fmac_f32_e32 v108, 0x3f317217, v109
	v_cmp_lt_f32_e64 s[0:1], |v109|, s73
	v_add_f32_e32 v110, 1.0, v110
	s_nop 0
	v_cndmask_b32_e64 v108, v109, v108, s[0:1]
	v_cndmask_b32_e32 v109, 0, v244, vcc
	v_cmp_gt_f32_e32 vcc, s65, v110
	v_sub_f32_e32 v140, v108, v109
	v_mul_f32_e64 v109, |v107|, s68
	v_cndmask_b32_e64 v111, 0, 32, vcc
	v_ldexp_f32 v110, v110, v111
	v_log_f32_e32 v110, v110
	v_max_f32_e32 v108, v106, v106
	v_exp_f32_e32 v109, v109
	v_max_f32_e32 v144, 0, v108
	v_mul_f32_e32 v108, 0x3f317217, v110
	v_fma_f32 v108, v110, s72, -v108
	v_fmac_f32_e32 v108, 0x3377d1cf, v110
	v_fmac_f32_e32 v108, 0x3f317217, v110
; __device__ __forceinline__ float softplusf(float z) { return fmaxf(z, 0.f) + __logf(1.f + __expf(-fabsf(z))); }
; __global__ void __launch_bounds__(512, 2) fwd_megakernel(Params kp_) {
;     ...
;                                         for (int kt = 0; kt < 4; ++kt) {
;                                             float sp[4];
; #pragma unroll
;                                             for (int j = 0; j < 4; ++j) { const float z = sa[kt][j]; const bool act = (kbase + kt * 16 + g4 * 4 + j) < tqi; const float s1 = softplusf(z);
;                                                 sp[j] = act ? s1 : 0.f; sa[kt][j] = act ? (z - s1) : -1e30f; }
;                                             const float s2 = sp[3], s1b = s2 + sp[2], s0 = s1b + sp[1];
;                                             T[kt] = s0 + sp[0];
;                                             sa[kt][0] -= s0; sa[kt][1] -= s1b; sa[kt][2] -= s2;
;                                         }
	v_cmp_lt_f32_e64 s[0:1], |v110|, s73
	v_add_f32_e32 v109, 1.0, v109
	s_nop 0
	v_cndmask_b32_e64 v108, v110, v108, s[0:1]
	v_cndmask_b32_e32 v110, 0, v244, vcc
	v_cmp_gt_f32_e32 vcc, s65, v109
	v_sub_f32_e32 v152, v108, v110
	v_mul_f32_e64 v110, |v96|, s68
	v_cndmask_b32_e64 v111, 0, 32, vcc
	v_ldexp_f32 v109, v109, v111
	v_log_f32_e32 v109, v109
	v_max_f32_e32 v108, v107, v107
	v_exp_f32_e32 v110, v110
	v_max_f32_e32 v138, 0, v108
	v_mul_f32_e32 v108, 0x3f317217, v109
	v_fma_f32 v108, v109, s72, -v108
	v_fmac_f32_e32 v108, 0x3377d1cf, v109
	v_fmac_f32_e32 v108, 0x3f317217, v109
	v_cmp_lt_f32_e64 s[0:1], |v109|, s73
	v_add_f32_e32 v110, 1.0, v110
	s_nop 0
	v_cndmask_b32_e64 v108, v109, v108, s[0:1]
	v_cndmask_b32_e32 v109, 0, v244, vcc
	v_cmp_gt_f32_e32 vcc, s65, v110
	v_sub_f32_e32 v146, v108, v109
	v_mul_f32_e64 v109, |v97|, s68
	v_cndmask_b32_e64 v111, 0, 32, vcc
	v_ldexp_f32 v110, v110, v111
	v_log_f32_e32 v110, v110
	v_max_f32_e32 v108, v96, v96
	v_exp_f32_e32 v109, v109
	v_max_f32_e32 v142, 0, v108
	v_mul_f32_e32 v108, 0x3f317217, v110
	v_fma_f32 v108, v110, s72, -v108
	v_fmac_f32_e32 v108, 0x3377d1cf, v110
	v_fmac_f32_e32 v108, 0x3f317217, v110
	v_cmp_lt_f32_e64 s[0:1], |v110|, s73
	v_add_f32_e32 v109, 1.0, v109
	s_nop 0
	v_cndmask_b32_e64 v108, v110, v108, s[0:1]
	v_cndmask_b32_e32 v110, 0, v244, vcc
	v_cmp_gt_f32_e32 vcc, s65, v109
	v_sub_f32_e32 v150, v108, v110
	v_mul_f32_e64 v110, |v98|, s68
	v_cndmask_b32_e64 v111, 0, 32, vcc
	v_ldexp_f32 v109, v109, v111
	v_log_f32_e32 v109, v109
	v_max_f32_e32 v108, v97, v97
	v_exp_f32_e32 v110, v110
	v_max_f32_e32 v148, 0, v108
	v_mul_f32_e32 v108, 0x3f317217, v109
	v_fma_f32 v108, v109, s72, -v108
	v_fmac_f32_e32 v108, 0x3377d1cf, v109
	v_fmac_f32_e32 v108, 0x3f317217, v109
	v_cmp_lt_f32_e64 s[0:1], |v109|, s73
	v_add_f32_e32 v110, 1.0, v110
	s_nop 0
	v_cndmask_b32_e64 v108, v109, v108, s[0:1]
	v_cndmask_b32_e32 v109, 0, v244, vcc
	v_cmp_gt_f32_e32 vcc, s65, v110
	v_sub_f32_e32 v156, v108, v109
	v_mul_f32_e64 v109, |v99|, s68
	v_cndmask_b32_e64 v111, 0, 32, vcc
	v_ldexp_f32 v110, v110, v111
	v_log_f32_e32 v110, v110
	v_max_f32_e32 v108, v98, v98
	v_exp_f32_e32 v109, v109
	v_max_f32_e32 v160, 0, v108
	v_mul_f32_e32 v108, 0x3f317217, v110
	v_fma_f32 v108, v110, s72, -v108
	v_fmac_f32_e32 v108, 0x3377d1cf, v110
	v_fmac_f32_e32 v108, 0x3f317217, v110
	v_cmp_lt_f32_e64 s[0:1], |v110|, s73
	v_add_f32_e32 v109, 1.0, v109
	s_nop 0
	v_cndmask_b32_e64 v108, v110, v108, s[0:1]
	v_cndmask_b32_e32 v110, 0, v244, vcc
	v_cmp_gt_f32_e32 vcc, s65, v109
	v_sub_f32_e32 v168, v108, v110
	v_mul_f32_e64 v110, |v92|, s68
	v_cndmask_b32_e64 v111, 0, 32, vcc
	v_ldexp_f32 v109, v109, v111
	v_log_f32_e32 v109, v109
	v_max_f32_e32 v108, v99, v99
	v_exp_f32_e32 v110, v110
	v_max_f32_e32 v154, 0, v108
	v_mul_f32_e32 v108, 0x3f317217, v109
	v_fma_f32 v108, v109, s72, -v108
	v_fmac_f32_e32 v108, 0x3377d1cf, v109
	v_fmac_f32_e32 v108, 0x3f317217, v109
	v_cmp_lt_f32_e64 s[0:1], |v109|, s73
	v_add_f32_e32 v110, 1.0, v110
	s_nop 0
	v_cndmask_b32_e64 v108, v109, v108, s[0:1]
	v_cndmask_b32_e32 v109, 0, v244, vcc
	v_cmp_gt_f32_e32 vcc, s65, v110
	v_sub_f32_e32 v162, v108, v109
	v_mul_f32_e64 v109, |v93|, s68
	v_cndmask_b32_e64 v111, 0, 32, vcc
	v_ldexp_f32 v110, v110, v111
	v_log_f32_e32 v110, v110
	v_max_f32_e32 v108, v92, v92
	v_exp_f32_e32 v109, v109
	v_max_f32_e32 v158, 0, v108
	v_mul_f32_e32 v108, 0x3f317217, v110
	v_fma_f32 v108, v110, s72, -v108
	v_fmac_f32_e32 v108, 0x3377d1cf, v110
	v_fmac_f32_e32 v108, 0x3f317217, v110
	v_cmp_lt_f32_e64 s[0:1], |v110|, s73
	v_add_f32_e32 v109, 1.0, v109
	s_nop 0
	v_cndmask_b32_e64 v108, v110, v108, s[0:1]
	v_cndmask_b32_e32 v110, 0, v244, vcc
	v_cmp_gt_f32_e32 vcc, s65, v109
	v_sub_f32_e32 v166, v108, v110
	v_mul_f32_e64 v110, |v94|, s68
	v_cndmask_b32_e64 v111, 0, 32, vcc
	v_ldexp_f32 v109, v109, v111
	v_log_f32_e32 v109, v109
	v_max_f32_e32 v108, v93, v93
	v_exp_f32_e32 v110, v110
	v_max_f32_e32 v164, 0, v108
	v_mul_f32_e32 v108, 0x3f317217, v109
	v_fma_f32 v108, v109, s72, -v108
	v_fmac_f32_e32 v108, 0x3377d1cf, v109
	v_fmac_f32_e32 v108, 0x3f317217, v109
	v_cmp_lt_f32_e64 s[0:1], |v109|, s73
	v_add_f32_e32 v110, 1.0, v110
	s_nop 0
	v_cndmask_b32_e64 v108, v109, v108, s[0:1]
	v_cndmask_b32_e32 v109, 0, v244, vcc
	v_cmp_gt_f32_e32 vcc, s65, v110
	v_sub_f32_e32 v172, v108, v109
	v_mul_f32_e64 v109, |v95|, s68
	v_cndmask_b32_e64 v111, 0, 32, vcc
	v_ldexp_f32 v110, v110, v111
	v_log_f32_e32 v110, v110
	v_max_f32_e32 v108, v94, v94
	v_exp_f32_e32 v109, v109
	v_max_f32_e32 v176, 0, v108
	v_mul_f32_e32 v108, 0x3f317217, v110
	v_fma_f32 v108, v110, s72, -v108
	v_fmac_f32_e32 v108, 0x3377d1cf, v110
	v_fmac_f32_e32 v108, 0x3f317217, v110
	v_cmp_lt_f32_e64 s[0:1], |v110|, s73
	v_add_f32_e32 v109, 1.0, v109
	s_nop 0
	v_cndmask_b32_e64 v108, v110, v108, s[0:1]
	v_cndmask_b32_e32 v110, 0, v244, vcc
	v_cmp_gt_f32_e32 vcc, s65, v109
	v_sub_f32_e32 v184, v108, v110
	v_mul_f32_e64 v110, |v100|, s68
	v_cndmask_b32_e64 v111, 0, 32, vcc
	v_ldexp_f32 v109, v109, v111
	v_log_f32_e32 v109, v109
	v_max_f32_e32 v108, v95, v95
	v_exp_f32_e32 v110, v110
	v_max_f32_e32 v170, 0, v108
	v_mul_f32_e32 v108, 0x3f317217, v109
	v_fma_f32 v108, v109, s72, -v108
	v_fmac_f32_e32 v108, 0x3377d1cf, v109
	v_fmac_f32_e32 v108, 0x3f317217, v109
	v_cmp_lt_f32_e64 s[0:1], |v109|, s73
	v_add_f32_e32 v110, 1.0, v110
	s_nop 0
	v_cndmask_b32_e64 v108, v109, v108, s[0:1]
	v_cndmask_b32_e32 v109, 0, v244, vcc
	v_cmp_gt_f32_e32 vcc, s65, v110
	v_sub_f32_e32 v178, v108, v109
	v_mul_f32_e64 v109, |v101|, s68
	v_cndmask_b32_e64 v111, 0, 32, vcc
	v_ldexp_f32 v110, v110, v111
	v_log_f32_e32 v110, v110
	v_max_f32_e32 v108, v100, v100
; #define SHX(v, o) shfl_idx((v), lane ^ (o))
; #define SHD(v, o) shfl_idx((v), lane + (o))
; __device__ __forceinline__ float softplusf(float z) { return fmaxf(z, 0.f) + __logf(1.f + __expf(-fabsf(z))); }
; __global__ void __launch_bounds__(512, 2) fwd_megakernel(Params kp_) {
;     ...
;                                         for (int kt = 0; kt < 4; ++kt) {
;                                             float sp[4];
; #pragma unroll
;                                             for (int j = 0; j < 4; ++j) { const float z = sa[kt][j]; const bool act = (kbase + kt * 16 + g4 * 4 + j) < tqi; const float s1 = softplusf(z);
;                                                 sp[j] = act ? s1 : 0.f; sa[kt][j] = act ? (z - s1) : -1e30f; }
;                                             const float s2 = sp[3], s1b = s2 + sp[2], s0 = s1b + sp[1];
;                                             T[kt] = s0 + sp[0];
;                                             sa[kt][0] -= s0; sa[kt][1] -= s1b; sa[kt][2] -= s2;
;                                         }
;                                         float kacc = Rq[qt];
; #pragma unroll
;     ...
;                                             const float d1 = SHD(T[kt], 16), d2 = SHD(T[kt], 32), d3 = SHD(T[kt], 48);
;                                             const float E = (g4 < 3 ? d1 : 0.f) + (g4 < 2 ? d2 : 0.f) + (g4 < 1 ? d3 : 0.f);
;                                             const float off = kacc + E;
; #pragma unroll
;                                             for (int j = 0; j < 4; ++j) sa[kt][j] = __expf(sa[kt][j] - off);
;                                             float tt = T[kt]; tt += SHX(tt, 16); tt += SHX(tt, 32);
;                                             kacc += tt;
;                                         }
;                                         Rq[qt] = kacc;
	v_exp_f32_e32 v109, v109
	v_max_f32_e32 v174, 0, v108
	v_mul_f32_e32 v108, 0x3f317217, v110
	v_fma_f32 v108, v110, s72, -v108
	v_fmac_f32_e32 v108, 0x3377d1cf, v110
	v_fmac_f32_e32 v108, 0x3f317217, v110
	v_cmp_lt_f32_e64 s[0:1], |v110|, s73
	v_add_f32_e32 v109, 1.0, v109
	s_nop 0
	v_cndmask_b32_e64 v108, v110, v108, s[0:1]
	v_cndmask_b32_e32 v110, 0, v244, vcc
	v_cmp_gt_f32_e32 vcc, s65, v109
	v_sub_f32_e32 v182, v108, v110
	v_mul_f32_e64 v110, |v102|, s68
	v_cndmask_b32_e64 v111, 0, 32, vcc
	v_ldexp_f32 v109, v109, v111
	v_log_f32_e32 v109, v109
	v_max_f32_e32 v108, v101, v101
	v_exp_f32_e32 v110, v110
	v_max_f32_e32 v180, 0, v108
	v_mul_f32_e32 v108, 0x3f317217, v109
	v_fma_f32 v108, v109, s72, -v108
	v_fmac_f32_e32 v108, 0x3377d1cf, v109
	v_fmac_f32_e32 v108, 0x3f317217, v109
	v_cmp_lt_f32_e64 s[0:1], |v109|, s73
	v_add_f32_e32 v110, 1.0, v110
	s_nop 0
	v_cndmask_b32_e64 v108, v109, v108, s[0:1]
	v_cndmask_b32_e32 v109, 0, v244, vcc
	v_cmp_gt_f32_e32 vcc, s65, v110
	v_sub_f32_e32 v188, v108, v109
	v_mul_f32_e64 v109, |v103|, s68
	v_cndmask_b32_e64 v111, 0, 32, vcc
	v_ldexp_f32 v110, v110, v111
	v_log_f32_e32 v110, v110
	v_max_f32_e32 v108, v102, v102
	v_exp_f32_e32 v109, v109
	v_max_f32_e32 v190, 0, v108
	v_mul_f32_e32 v108, 0x3f317217, v110
	v_fma_f32 v108, v110, s72, -v108
	v_fmac_f32_e32 v108, 0x3377d1cf, v110
	v_fmac_f32_e32 v108, 0x3f317217, v110
	v_cmp_lt_f32_e64 s[0:1], |v110|, s73
	v_add_f32_e32 v109, 1.0, v109
	s_nop 0
	v_cndmask_b32_e64 v108, v110, v108, s[0:1]
	v_cndmask_b32_e32 v110, 0, v244, vcc
	v_cmp_gt_f32_e32 vcc, s65, v109
	v_sub_f32_e32 v194, v108, v110
	v_max_f32_e32 v108, v103, v103
	v_cndmask_b32_e64 v111, 0, 32, vcc
	v_ldexp_f32 v109, v109, v111
	v_log_f32_e32 v109, v109
	v_max_f32_e32 v186, 0, v108
	v_pk_add_f32 v[110:111], v[134:135], v[140:141]
	v_or_b32_e32 v134, 2, v219
	v_mul_f32_e32 v108, 0x3f317217, v109
	v_fma_f32 v108, v109, s72, -v108
	v_fmac_f32_e32 v108, 0x3377d1cf, v109
	v_fmac_f32_e32 v108, 0x3f317217, v109
	v_cmp_lt_f32_e64 s[0:1], |v109|, s73
	v_or_b32_e32 v135, 3, v219
	v_cmp_lt_i32_e64 s[14:15], v135, v117
	v_cndmask_b32_e64 v108, v109, v108, s[0:1]
	v_cndmask_b32_e32 v109, 0, v244, vcc
	v_sub_f32_e32 v192, v108, v109
	v_pk_add_f32 v[108:109], v[132:133], v[136:137]
	v_cmp_lt_i32_e32 vcc, v221, v117
	v_sub_f32_e32 v88, v88, v109
	v_cndmask_b32_e64 v200, v246, v88, s[24:25]
	v_sub_f32_e32 v88, v89, v111
	v_cndmask_b32_e32 v140, v246, v88, vcc
	v_pk_add_f32 v[88:89], v[138:139], v[146:147]
	v_cmp_lt_i32_e64 s[0:1], v134, v117
	v_sub_f32_e32 v90, v90, v89
	v_pk_add_f32 v[132:133], v[144:145], v[152:153]
	v_cndmask_b32_e64 v141, v246, v90, s[0:1]
	v_sub_f32_e32 v90, v91, v133
	v_cndmask_b32_e64 v202, v246, v90, s[14:15]
	v_cndmask_b32_e64 v139, 0, v133, s[14:15]
	v_cmp_lt_i32_e64 s[14:15], v134, v124
	v_cmp_lt_i32_e64 s[16:17], v135, v124
	v_cndmask_b32_e64 v91, 0, v89, s[0:1]
	v_cndmask_b32_e64 v138, 0, v132, s[14:15]
	v_cndmask_b32_e64 v90, 0, v88, s[16:17]
	v_cndmask_b32_e32 v137, 0, v111, vcc
	v_pk_add_f32 v[134:135], v[90:91], v[138:139]
	v_sub_f32_e32 v111, v141, v139
	v_pk_add_f32 v[138:139], v[142:143], v[150:151]
	v_cmp_lt_i32_e32 vcc, v221, v124
	v_sub_f32_e32 v91, v140, v135
	v_sub_f32_e32 v64, v64, v139
	v_pk_add_f32 v[140:141], v[148:149], v[156:157]
	v_cndmask_b32_e32 v136, 0, v110, vcc
	v_cndmask_b32_e64 v133, v246, v64, s[40:41]
	v_sub_f32_e32 v64, v65, v141
	v_cmp_lt_i32_e64 s[0:1], v222, v117
	v_pk_add_f32 v[136:137], v[134:135], v[136:137]
	v_or_b32_e32 v144, 18, v219
	v_cndmask_b32_e64 v135, v246, v64, s[0:1]
	v_pk_add_f32 v[64:65], v[154:155], v[162:163]
	v_or_b32_e32 v145, 19, v219
	v_sub_f32_e32 v66, v66, v65
	v_cmp_lt_i32_e64 s[22:23], v144, v117
	v_pk_add_f32 v[142:143], v[160:161], v[168:169]
	v_cmp_lt_i32_e64 s[20:21], v145, v117
	v_cndmask_b32_e64 v150, v246, v66, s[22:23]
	v_sub_f32_e32 v66, v67, v143
	v_sub_f32_e32 v89, v200, v137
	v_cndmask_b32_e64 v200, v246, v66, s[20:21]
	v_cndmask_b32_e64 v149, 0, v143, s[20:21]
	v_cmp_lt_i32_e64 s[20:21], v144, v124
	v_cndmask_b32_e64 v67, 0, v65, s[22:23]
	v_cmp_lt_i32_e64 s[22:23], v145, v124
	v_cndmask_b32_e64 v148, 0, v142, s[20:21]
	v_cndmask_b32_e64 v147, 0, v141, s[0:1]
	v_cndmask_b32_e64 v66, 0, v64, s[22:23]
	v_cndmask_b32_e64 v146, 0, v140, s[18:19]
	v_pk_add_f32 v[144:145], v[66:67], v[148:149]
	v_cmp_lt_i32_e64 s[0:1], v227, v117
	v_pk_add_f32 v[146:147], v[144:145], v[146:147]
	v_sub_f32_e32 v67, v135, v145
	v_sub_f32_e32 v65, v133, v147
	v_sub_f32_e32 v133, v150, v149
	v_pk_add_f32 v[148:149], v[158:159], v[166:167]
	v_pk_add_f32 v[150:151], v[164:165], v[172:173]
	v_sub_f32_e32 v60, v60, v149
	v_cndmask_b32_e64 v135, v246, v60, s[44:45]
	v_sub_f32_e32 v60, v61, v151
	v_cndmask_b32_e64 v141, v246, v60, s[0:1]
	v_pk_add_f32 v[60:61], v[170:171], v[178:179]
	v_or_b32_e32 v143, 34, v219
	v_sub_f32_e32 v62, v62, v61
	v_or_b32_e32 v145, 35, v219
	v_cmp_lt_i32_e64 s[30:31], v143, v117
	v_pk_add_f32 v[152:153], v[176:177], v[184:185]
	v_cmp_lt_i32_e64 s[28:29], v145, v117
	v_cndmask_b32_e64 v160, v246, v62, s[30:31]
	v_sub_f32_e32 v62, v63, v153
	v_cndmask_b32_e64 v176, v246, v62, s[28:29]
	v_cndmask_b32_e64 v159, 0, v153, s[28:29]
	v_cmp_lt_i32_e64 s[28:29], v143, v124
	v_cndmask_b32_e64 v63, 0, v61, s[30:31]
	v_cmp_lt_i32_e64 s[30:31], v145, v124
	v_cndmask_b32_e64 v158, 0, v152, s[28:29]
	v_cndmask_b32_e64 v157, 0, v151, s[0:1]
	v_cndmask_b32_e64 v62, 0, v60, s[30:31]
	v_cndmask_b32_e64 v156, 0, v150, s[26:27]
	v_pk_add_f32 v[154:155], v[62:63], v[158:159]
	v_cmp_lt_i32_e64 s[0:1], v228, v117
	v_pk_add_f32 v[156:157], v[154:155], v[156:157]
	v_sub_f32_e32 v63, v141, v155
	v_sub_f32_e32 v61, v135, v157
; __device__ __forceinline__ unsigned pk2(float lo, float hi) { const f32x2_t v = {lo, hi}; const bf16x2_t b = __builtin_convertvector(v, bf16x2_t); return __builtin_bit_cast(unsigned, b); }
; #define SHX(v, o) shfl_idx((v), lane ^ (o))
; #define SHD(v, o) shfl_idx((v), lane + (o))
; #define MFMA16(a, b, c) __builtin_amdgcn_mfma_f32_16x16x32_bf16((a), (b), (c), 0, 0, 0)
; __global__ void __launch_bounds__(512, 2) fwd_megakernel(Params kp_) {
;     ...
;                                         float kacc = Rq[qt];
; #pragma unroll
;     ...
;                                             const float d1 = SHD(T[kt], 16), d2 = SHD(T[kt], 32), d3 = SHD(T[kt], 48);
;                                             const float E = (g4 < 3 ? d1 : 0.f) + (g4 < 2 ? d2 : 0.f) + (g4 < 1 ? d3 : 0.f);
;                                             const float off = kacc + E;
; #pragma unroll
;                                             for (int j = 0; j < 4; ++j) sa[kt][j] = __expf(sa[kt][j] - off);
;                                             float tt = T[kt]; tt += SHX(tt, 16); tt += SHX(tt, 32);
;                                             kacc += tt;
;                                         }
;                                         Rq[qt] = kacc;
; #pragma unroll
;                                         for (int hf = 0; hf < 2; ++hf) {
;                                             u32x4 pw; pw.x = pk2(sa[2 * hf][0], sa[2 * hf][1]); pw.y = pk2(sa[2 * hf][2], sa[2 * hf][3]); pw.z = pk2(sa[2 * hf + 1][0], sa[2 * hf + 1][1]); pw.w = pk2(sa[2 * hf + 1][2], sa[2 * hf + 1][3]);
;                                             const bf16x8 pb = __builtin_bit_cast(bf16x8, pw);
; #pragma unroll
;                                             for (int dt = 0; dt < 4; ++dt) {
;                                                 const bf16* vp = VTb + (dt * 16 + r16) * 72 + hf * 32 + g4 * 4;
;                                                 const u32x2 v0 = *(const u32x2*)vp, v1 = *(const u32x2*)(vp + 16);
;                                                 u32x4 vw4; vw4.x = v0.x; vw4.y = v0.y; vw4.z = v1.x; vw4.w = v1.y;
;                                                 oacc[dt][qt] = MFMA16(__builtin_bit_cast(bf16x8, vw4), pb, oacc[dt][qt]);
;                                             }
;                                         }
	v_sub_f32_e32 v135, v160, v159
	v_pk_add_f32 v[158:159], v[174:175], v[182:183]
	v_pk_add_f32 v[160:161], v[180:181], v[188:189]
	v_sub_f32_e32 v56, v56, v159
	v_cndmask_b32_e64 v141, v246, v56, s[0:1]
	v_sub_f32_e32 v56, v57, v161
	v_cndmask_b32_e64 v143, v246, v56, s[34:35]
	v_pk_add_f32 v[56:57], v[186:187], v[192:193]
	v_pk_add_f32 v[162:163], v[190:191], v[194:195]
	v_sub_f32_e32 v58, v58, v57
	v_cndmask_b32_e64 v145, v246, v58, s[38:39]
	v_sub_f32_e32 v58, v59, v163
	v_cndmask_b32_e64 v151, v246, v58, s[36:37]
	v_cndmask_b32_e64 v169, 0, v163, s[36:37]
	v_cmp_lt_i32_e64 s[36:37], v230, v124
	v_cndmask_b32_e64 v59, 0, v57, s[38:39]
	v_cmp_lt_i32_e64 s[38:39], v231, v124
	v_cndmask_b32_e64 v167, 0, v161, s[34:35]
	v_cmp_lt_i32_e64 s[34:35], v229, v124
	v_cndmask_b32_e64 v168, 0, v162, s[36:37]
	v_cndmask_b32_e64 v58, 0, v56, s[38:39]
	v_cndmask_b32_e64 v166, 0, v160, s[34:35]
	v_pk_add_f32 v[164:165], v[58:59], v[168:169]
	v_cndmask_b32_e64 v171, 0, v159, s[0:1]
	v_pk_add_f32 v[166:167], v[164:165], v[166:167]
	v_cndmask_b32_e64 v170, 0, v158, s[42:43]
	v_pk_add_f32 v[170:171], v[166:167], v[170:171]
	v_sub_f32_e32 v145, v145, v169
	ds_bpermute_b32 v169, v127, v171
	ds_bpermute_b32 v168, v127, v170
	v_cndmask_b32_e64 v173, 0, v149, s[44:45]
	v_cmp_lt_i32_e64 s[44:45], v220, v124
	v_sub_f32_e32 v57, v141, v167
	ds_bpermute_b32 v59, v210, v171
	ds_bpermute_b32 v141, v211, v171
	v_cndmask_b32_e64 v172, 0, v148, s[44:45]
	s_waitcnt lgkmcnt(2)
	v_pk_add_f32 v[168:169], v[170:171], v[168:169]
	ds_bpermute_b32 v153, v212, v171
	v_pk_add_f32 v[188:189], v[156:157], v[172:173]
	ds_bpermute_b32 v173, v206, v169
	ds_bpermute_b32 v172, v206, v168
	s_waitcnt lgkmcnt(4)
	v_cndmask_b32_e64 v59, v59, 0, s[6:7]
	s_waitcnt lgkmcnt(3)
	v_cndmask_b32_e64 v141, 0, v141, s[8:9]
	v_add_f32_e32 v59, v59, v141
	s_waitcnt lgkmcnt(2)
	v_cndmask_b32_e64 v141, 0, v153, s[10:11]
	s_waitcnt lgkmcnt(0)
	v_pk_add_f32 v[168:169], v[168:169], v[172:173]
	v_add_f32_e32 v59, v59, v141
	v_pk_add_f32 v[190:191], v[130:131], v[168:169]
	ds_bpermute_b32 v169, v127, v189
	ds_bpermute_b32 v168, v127, v188
	v_sub_f32_e32 v143, v143, v165
	v_add_f32_e32 v59, v131, v59
	v_sub_f32_e32 v141, v143, v59
	v_sub_f32_e32 v143, v145, v59
	ds_bpermute_b32 v145, v210, v189
	ds_bpermute_b32 v149, v211, v189
	v_sub_f32_e32 v57, v57, v59
	v_sub_f32_e32 v59, v151, v59
	ds_bpermute_b32 v151, v212, v189
	v_cndmask_b32_e64 v173, 0, v139, s[40:41]
	v_cmp_lt_i32_e64 s[40:41], v219, v126
	s_waitcnt lgkmcnt(3)
	v_pk_add_f32 v[168:169], v[188:189], v[168:169]
	s_waitcnt lgkmcnt(2)
	v_cndmask_b32_e64 v145, v145, 0, s[6:7]
	v_cndmask_b32_e64 v172, 0, v138, s[40:41]
	v_pk_add_f32 v[192:193], v[146:147], v[172:173]
	ds_bpermute_b32 v173, v206, v169
	ds_bpermute_b32 v172, v206, v168
	s_waitcnt lgkmcnt(3)
	v_cndmask_b32_e64 v149, 0, v149, s[8:9]
	v_add_f32_e32 v145, v145, v149
	s_waitcnt lgkmcnt(2)
	v_cndmask_b32_e64 v149, 0, v151, s[10:11]
	v_add_f32_e32 v145, v145, v149
	v_add_f32_e32 v131, v191, v145
	ds_bpermute_b32 v139, v210, v193
	ds_bpermute_b32 v145, v211, v193
	ds_bpermute_b32 v147, v212, v193
	s_waitcnt lgkmcnt(3)
	v_pk_add_f32 v[168:169], v[168:169], v[172:173]
	ds_bpermute_b32 v173, v127, v193
	ds_bpermute_b32 v172, v127, v192
	v_cmp_lt_i32_e64 s[0:1], v219, v124
	v_pk_add_f32 v[194:195], v[190:191], v[168:169]
	v_cndmask_b32_e64 v169, 0, v109, s[24:25]
	v_cndmask_b32_e64 v168, 0, v108, s[0:1]
	s_waitcnt lgkmcnt(4)
	v_cndmask_b32_e64 v139, v139, 0, s[6:7]
	s_waitcnt lgkmcnt(3)
	v_cndmask_b32_e64 v145, 0, v145, s[8:9]
	v_pk_add_f32 v[168:169], v[136:137], v[168:169]
	v_add_f32_e32 v139, v139, v145
	s_waitcnt lgkmcnt(2)
	v_cndmask_b32_e64 v145, 0, v147, s[10:11]
	ds_bpermute_b32 v109, v210, v169
	s_waitcnt lgkmcnt(1)
	v_pk_add_f32 v[172:173], v[192:193], v[172:173]
	ds_bpermute_b32 v137, v211, v169
	v_add_f32_e32 v139, v139, v145
	ds_bpermute_b32 v175, v206, v173
	ds_bpermute_b32 v145, v212, v169
	ds_bpermute_b32 v174, v206, v172
	s_waitcnt lgkmcnt(4)
	v_cndmask_b32_e64 v109, v109, 0, s[6:7]
	s_waitcnt lgkmcnt(3)
	v_cndmask_b32_e64 v137, 0, v137, s[8:9]
	v_add_f32_e32 v139, v195, v139
	v_add_f32_e32 v109, v109, v137
	s_waitcnt lgkmcnt(1)
	v_cndmask_b32_e64 v137, 0, v145, s[10:11]
	s_waitcnt lgkmcnt(0)
	v_pk_add_f32 v[172:173], v[172:173], v[174:175]
	v_sub_f32_e32 v65, v65, v139
	v_sub_f32_e32 v67, v67, v139
	v_sub_f32_e32 v133, v133, v139
	v_sub_f32_e32 v139, v200, v139
	v_add_f32_e32 v109, v109, v137
	v_pk_add_f32 v[200:201], v[194:195], v[172:173]
	v_sub_f32_e32 v61, v61, v131
	v_add_f32_e32 v109, v201, v109
	v_sub_f32_e32 v89, v89, v109
	v_sub_f32_e32 v91, v91, v109
	v_sub_f32_e32 v111, v111, v109
	v_sub_f32_e32 v109, v202, v109
	v_sub_f32_e32 v63, v63, v131
	v_mul_f32_e32 v65, 0x3fb8aa3b, v65
	v_mul_f32_e32 v67, 0x3fb8aa3b, v67
	v_mul_f32_e32 v133, 0x3fb8aa3b, v133
	v_mul_f32_e32 v89, 0x3fb8aa3b, v89
	v_mul_f32_e32 v91, 0x3fb8aa3b, v91
	v_mul_f32_e32 v111, 0x3fb8aa3b, v111
	v_mul_f32_e32 v109, 0x3fb8aa3b, v109
	v_mul_f32_e32 v137, 0x3fb8aa3b, v139
	v_mul_f32_e32 v61, 0x3fb8aa3b, v61
	v_exp_f32_e32 v65, v65
	v_exp_f32_e32 v67, v67
	v_exp_f32_e32 v133, v133
	v_exp_f32_e32 v89, v89
	v_exp_f32_e32 v91, v91
	v_exp_f32_e32 v111, v111
	v_exp_f32_e32 v109, v109
	v_exp_f32_e32 v137, v137
	v_mul_f32_e32 v63, 0x3fb8aa3b, v63
	v_exp_f32_e32 v61, v61
	v_exp_f32_e32 v63, v63
	v_cvt_pk_bf16_f32 v172, v89, v91
	v_cvt_pk_bf16_f32 v173, v111, v109
	v_cvt_pk_bf16_f32 v174, v65, v67
	v_cvt_pk_bf16_f32 v175, v133, v137
	v_sub_f32_e32 v89, v93, v150
	ds_bpermute_b32 v93, v210, v170
	v_mfma_f32_16x16x32_bf16 v[40:43], v[80:83], v[172:175], v[40:43]
	v_sub_f32_e32 v60, v95, v60
	ds_bpermute_b32 v95, v212, v170
	v_sub_f32_e32 v91, v101, v160
	v_mfma_f32_16x16x32_bf16 v[44:47], v[76:79], v[172:175], v[44:47]
	v_cndmask_b32_e64 v91, v246, v91, s[34:35]
	v_sub_f32_e32 v56, v103, v56
	v_cndmask_b32_e64 v56, v246, v56, s[38:39]
	v_mfma_f32_16x16x32_bf16 v[36:39], v[72:75], v[172:175], v[36:39]
	v_sub_f32_e32 v91, v91, v164
	v_sub_f32_e32 v65, v135, v131
	v_sub_f32_e32 v67, v176, v131
	v_mfma_f32_16x16x32_bf16 v[32:35], v[84:87], v[172:175], v[32:35]
	v_cvt_pk_bf16_f32 v172, v61, v63
	v_sub_f32_e32 v61, v106, v132
	v_cndmask_b32_e64 v61, v246, v61, s[14:15]
	v_sub_f32_e32 v61, v61, v90
	v_sub_f32_e32 v90, v94, v152
	ds_bpermute_b32 v94, v211, v170
	v_sub_f32_e32 v63, v107, v88
	v_sub_f32_e32 v88, v98, v142
	v_cndmask_b32_e64 v88, v246, v88, s[20:21]
	v_sub_f32_e32 v66, v88, v66
	v_sub_f32_e32 v88, v92, v148
	v_sub_f32_e32 v92, v102, v162
	v_cndmask_b32_e64 v92, v246, v92, s[36:37]
	v_sub_f32_e32 v58, v92, v58
	s_waitcnt lgkmcnt(2)
; __device__ __forceinline__ unsigned pk2(float lo, float hi) { const f32x2_t v = {lo, hi}; const bf16x2_t b = __builtin_convertvector(v, bf16x2_t); return __builtin_bit_cast(unsigned, b); }
; #define SHX(v, o) shfl_idx((v), lane ^ (o))
; #define SHD(v, o) shfl_idx((v), lane + (o))
; #define MFMA16(a, b, c) __builtin_amdgcn_mfma_f32_16x16x32_bf16((a), (b), (c), 0, 0, 0)
; __global__ void __launch_bounds__(512, 2) fwd_megakernel(Params kp_) {
;     ...
;                                         float kacc = Rq[qt];
; #pragma unroll
;     ...
;                                             const float d1 = SHD(T[kt], 16), d2 = SHD(T[kt], 32), d3 = SHD(T[kt], 48);
;                                             const float E = (g4 < 3 ? d1 : 0.f) + (g4 < 2 ? d2 : 0.f) + (g4 < 1 ? d3 : 0.f);
;                                             const float off = kacc + E;
; #pragma unroll
;                                             for (int j = 0; j < 4; ++j) sa[kt][j] = __expf(sa[kt][j] - off);
;                                             float tt = T[kt]; tt += SHX(tt, 16); tt += SHX(tt, 32);
;                                             kacc += tt;
;                                         }
;                                         Rq[qt] = kacc;
; #pragma unroll
;                                         for (int hf = 0; hf < 2; ++hf) {
;                                             u32x4 pw; pw.x = pk2(sa[2 * hf][0], sa[2 * hf][1]); pw.y = pk2(sa[2 * hf][2], sa[2 * hf][3]); pw.z = pk2(sa[2 * hf + 1][0], sa[2 * hf + 1][1]); pw.w = pk2(sa[2 * hf + 1][2], sa[2 * hf + 1][3]);
;                                             const bf16x8 pb = __builtin_bit_cast(bf16x8, pw);
; #pragma unroll
;                                             for (int dt = 0; dt < 4; ++dt) {
;                                                 const bf16* vp = VTb + (dt * 16 + r16) * 72 + hf * 32 + g4 * 4;
;                                                 const u32x2 v0 = *(const u32x2*)vp, v1 = *(const u32x2*)(vp + 16);
;                                                 u32x4 vw4; vw4.x = v0.x; vw4.y = v0.y; vw4.z = v1.x; vw4.w = v1.y;
;                                                 oacc[dt][qt] = MFMA16(__builtin_bit_cast(bf16x8, vw4), pb, oacc[dt][qt]);
;                                             }
;                                         }
	v_cndmask_b32_e64 v92, v93, 0, s[6:7]
	s_waitcnt lgkmcnt(0)
	v_cndmask_b32_e64 v93, 0, v94, s[8:9]
	v_add_f32_e32 v92, v92, v93
	v_cndmask_b32_e64 v93, 0, v95, s[10:11]
	v_add_f32_e32 v92, v92, v93
	v_cndmask_b32_e64 v90, v246, v90, s[28:29]
	v_add_f32_e32 v92, v130, v92
	v_sub_f32_e32 v62, v90, v62
	v_sub_f32_e32 v90, v100, v158
	v_sub_f32_e32 v58, v58, v92
	v_cndmask_b32_e64 v90, v246, v90, s[42:43]
	v_mul_f32_e32 v58, 0x3fb8aa3b, v58
	v_sub_f32_e32 v90, v90, v166
	v_exp_f32_e32 v93, v58
	ds_bpermute_b32 v58, v210, v188
	ds_bpermute_b32 v94, v211, v188
	v_sub_f32_e32 v90, v90, v92
	v_sub_f32_e32 v91, v91, v92
	v_sub_f32_e32 v56, v56, v92
	ds_bpermute_b32 v92, v212, v188
	v_mul_f32_e32 v95, 0x3fb8aa3b, v56
	s_waitcnt lgkmcnt(2)
	v_cndmask_b32_e64 v56, v58, 0, s[6:7]
	s_waitcnt lgkmcnt(1)
	v_cndmask_b32_e64 v58, 0, v94, s[8:9]
	v_add_f32_e32 v56, v56, v58
	s_waitcnt lgkmcnt(0)
	v_cndmask_b32_e64 v58, 0, v92, s[10:11]
	v_cndmask_b32_e64 v88, v246, v88, s[44:45]
	v_add_f32_e32 v56, v56, v58
	v_sub_f32_e32 v88, v88, v156
	v_add_f32_e32 v92, v190, v56
	v_sub_f32_e32 v56, v88, v92
	v_mul_f32_e32 v56, 0x3fb8aa3b, v56
	ds_bpermute_b32 v58, v210, v192
	ds_bpermute_b32 v88, v211, v192
	v_mul_f32_e32 v65, 0x3fb8aa3b, v65
	v_mul_f32_e32 v67, 0x3fb8aa3b, v67
	v_exp_f32_e32 v94, v56
	ds_bpermute_b32 v56, v212, v192
	v_exp_f32_e32 v65, v65
	v_exp_f32_e32 v67, v67
	s_waitcnt lgkmcnt(2)
	v_cndmask_b32_e64 v58, v58, 0, s[6:7]
	s_waitcnt lgkmcnt(1)
	v_cndmask_b32_e64 v88, 0, v88, s[8:9]
	v_add_f32_e32 v58, v58, v88
	v_cvt_pk_bf16_f32 v173, v65, v67
	v_sub_f32_e32 v65, v96, v138
	v_sub_f32_e32 v67, v97, v140
	s_waitcnt lgkmcnt(0)
	v_cndmask_b32_e64 v56, 0, v56, s[10:11]
	v_cndmask_b32_e64 v65, v246, v65, s[40:41]
	v_cndmask_b32_e64 v67, v246, v67, s[18:19]
	v_add_f32_e32 v56, v58, v56
	v_sub_f32_e32 v65, v65, v146
	v_sub_f32_e32 v67, v67, v144
	v_add_f32_e32 v56, v194, v56
	v_sub_f32_e32 v58, v65, v56
	v_sub_f32_e32 v65, v67, v56
	ds_bpermute_b32 v67, v210, v168
	ds_bpermute_b32 v88, v211, v168
	v_mul_f32_e32 v57, 0x3fb8aa3b, v57
	v_mul_f32_e32 v141, 0x3fb8aa3b, v141
	v_mul_f32_e32 v143, 0x3fb8aa3b, v143
	v_mul_f32_e32 v59, 0x3fb8aa3b, v59
	ds_bpermute_b32 v96, v212, v168
	v_exp_f32_e32 v57, v57
	v_exp_f32_e32 v141, v141
	v_exp_f32_e32 v143, v143
	v_exp_f32_e32 v59, v59
	v_sub_f32_e32 v64, v99, v64
	v_cndmask_b32_e64 v64, v246, v64, s[22:23]
	v_sub_f32_e32 v66, v66, v56
	v_sub_f32_e32 v56, v64, v56
	s_waitcnt lgkmcnt(2)
	v_cndmask_b32_e64 v64, v67, 0, s[6:7]
	s_waitcnt lgkmcnt(1)
	v_cndmask_b32_e64 v67, 0, v88, s[8:9]
	v_cvt_pk_bf16_f32 v174, v57, v141
	v_cvt_pk_bf16_f32 v175, v143, v59
	v_sub_f32_e32 v57, v104, v108
	v_sub_f32_e32 v59, v105, v110
	v_add_f32_e32 v64, v64, v67
	s_waitcnt lgkmcnt(0)
	v_cndmask_b32_e64 v67, 0, v96, s[10:11]
	v_cndmask_b32_e64 v57, v246, v57, s[0:1]
	v_cndmask_b32_e32 v59, v246, v59, vcc
	v_add_f32_e32 v64, v64, v67
	v_cndmask_b32_e64 v63, v246, v63, s[16:17]
	v_sub_f32_e32 v57, v57, v136
	v_sub_f32_e32 v59, v59, v134
	v_add_f32_e32 v64, v200, v64
	v_sub_f32_e32 v57, v57, v64
	v_sub_f32_e32 v59, v59, v64
	v_sub_f32_e32 v61, v61, v64
	v_sub_f32_e32 v63, v63, v64
	v_mul_f32_e32 v57, 0x3fb8aa3b, v57
	v_mul_f32_e32 v59, 0x3fb8aa3b, v59
	v_mul_f32_e32 v61, 0x3fb8aa3b, v61
	v_mul_f32_e32 v63, 0x3fb8aa3b, v63
	v_exp_f32_e32 v57, v57
	v_exp_f32_e32 v59, v59
	v_exp_f32_e32 v61, v61
	v_exp_f32_e32 v63, v63
	v_cndmask_b32_e64 v89, v246, v89, s[26:27]
	v_cndmask_b32_e64 v60, v246, v60, s[30:31]
	v_sub_f32_e32 v89, v89, v154
	v_sub_f32_e32 v89, v89, v92
	v_mul_f32_e32 v58, 0x3fb8aa3b, v58
	v_mul_f32_e32 v65, 0x3fb8aa3b, v65
	v_mul_f32_e32 v66, 0x3fb8aa3b, v66
	v_mul_f32_e32 v56, 0x3fb8aa3b, v56
	v_sub_f32_e32 v62, v62, v92
	v_sub_f32_e32 v60, v60, v92
	v_exp_f32_e32 v58, v58
	v_exp_f32_e32 v65, v65
	v_exp_f32_e32 v66, v66
	v_exp_f32_e32 v64, v56
	v_cvt_pk_bf16_f32 v56, v57, v59
	v_cvt_pk_bf16_f32 v57, v61, v63
	v_mul_f32_e32 v61, 0x3fb8aa3b, v89
	v_mul_f32_e32 v62, 0x3fb8aa3b, v62
	v_mul_f32_e32 v60, 0x3fb8aa3b, v60
	v_exp_f32_e32 v61, v61
	v_exp_f32_e32 v62, v62
	v_exp_f32_e32 v60, v60
	v_cvt_pk_bf16_f32 v58, v58, v65
	v_cvt_pk_bf16_f32 v59, v66, v64
	ds_read2_b64 v[176:179], v224 offset0:168 offset1:172
	ds_read2_b64 v[180:183], v225 offset0:200 offset1:204
	ds_read2_b64 v[184:187], v226 offset0:232 offset1:236
	v_mfma_f32_16x16x32_bf16 v[28:31], v[80:83], v[56:59], v[28:31]
	v_exp_f32_e32 v63, v95
	v_mul_f32_e32 v90, 0x3fb8aa3b, v90
	v_mul_f32_e32 v91, 0x3fb8aa3b, v91
	v_mfma_f32_16x16x32_bf16 v[24:27], v[76:79], v[56:59], v[24:27]
	v_exp_f32_e32 v90, v90
	v_exp_f32_e32 v91, v91
	s_mov_b32 s30, s54
	v_mfma_f32_16x16x32_bf16 v[16:19], v[72:75], v[56:59], v[16:19]
	v_mfma_f32_16x16x32_bf16 v[12:15], v[84:87], v[56:59], v[12:15]
	v_cvt_pk_bf16_f32 v56, v94, v61
	v_cvt_pk_bf16_f32 v57, v62, v60
	ds_bpermute_b32 v61, v127, v169
	ds_bpermute_b32 v60, v127, v168
	v_cvt_pk_bf16_f32 v59, v93, v63
	v_cvt_pk_bf16_f32 v58, v90, v91
	v_mfma_f32_16x16x32_bf16 v[40:43], v[68:71], v[172:175], v[40:43]
	s_waitcnt lgkmcnt(0)
	v_pk_add_f32 v[60:61], v[168:169], v[60:61]
	ds_bpermute_b32 v63, v206, v61
	ds_bpermute_b32 v62, v206, v60
	v_mfma_f32_16x16x32_bf16 v[44:47], v[176:179], v[172:175], v[44:47]
	s_waitcnt lgkmcnt(0)
	v_pk_add_f32 v[60:61], v[60:61], v[62:63]
	v_mfma_f32_16x16x32_bf16 v[36:39], v[180:183], v[172:175], v[36:39]
	v_add_f32_e64 v130, v200, v60
	v_add_f32_e64 v131, v201, v61
	v_mfma_f32_16x16x32_bf16 v[32:35], v[184:187], v[172:175], v[32:35]
	v_mfma_f32_16x16x32_bf16 v[28:31], v[68:71], v[56:59], v[28:31]
	v_mfma_f32_16x16x32_bf16 v[24:27], v[176:179], v[56:59], v[24:27]
	v_mfma_f32_16x16x32_bf16 v[16:19], v[180:183], v[56:59], v[16:19]
	v_mfma_f32_16x16x32_bf16 v[12:15], v[184:187], v[56:59], v[12:15]
